# GDN scan: LDS drain after the step-3 state-image write removed (loop-top staging writes follow without waiting)
# baseline (speedup 1.0000x reference)
; DI bf16x8 tr2(const bf16_t* p0, const bf16_t* p1) { s16x4 a = trread(p0), b = trread(p1); return __builtin_shufflevector(a, b, 0, 1, 2, 3, 4, 5, 6, 7); }
; DI f32x4 mfma16(bf16x8 a, bf16x8 b, f32x4 c) { return __builtin_amdgcn_mfma_f32_16x16x32_bf16(a, b, c, 0, 0, 0); }
; DI void gdn_scan_item(const P& p, int item, unsigned char* smem) {
;     ...
; #pragma unroll
;             for (int k2 = 0; k2 < 2; ++k2) acc = mfma16(Bv[k2], ld8(sAT + (16 * mt + l15) * 72 + 32 * k2 + 8 * g), acc);
;             bf16_t* ob = OG + (size_t)prow(b, dir, 64 * c) * 512 + 128 * h + 32 * cq;
;             u32x2 ov; ov.x = pk2(acc[0], acc[1]); ov.y = pk2(acc[2], acc[3]);
;             *(u32x2*)(ob + sgn * ((16 * mt + l15) * 512) + 16 * nt + 4 * g) = ov;
;         }
; #pragma unroll
;         for (int j = 0; j < 2; ++j) {
;             const int dt = 2 * mt + j;
;             st[j] *= dec;
; #pragma unroll
;             for (int k2 = 0; k2 < 2; ++k2) {
;                 const bf16x8 ak = tr2(sKO + (32 * k2 + 8 * g + q4) * 136 + 16 * dt + 4 * p4, sKO + (32 * k2 + 8 * g + 4 + q4) * 136 + 16 * dt + 4 * p4);
;                 st[j] = mfma16(ak, Bv[k2], st[j]);
;             }
;         }
;         sBS[(nt * 4 + mt) * 64 + lane] = __builtin_bit_cast(u32x4, packacc(st[0], st[1]));
;     };
;     GdnRegs R0, R1, R2;
;     loadr(R0, 0); loadr(R1, 1); loadr(R2, 2);
; #pragma unroll 1
;     for (int c = 0; c < 36; c += 3) { step(R0, c); step(R1, c + 1); step(R2, c + 2); }
.LBB0_500:
	ds_read_b64_tr_b16 v[226:227], v187 offset:35904
	ds_read_b64_tr_b16 v[224:225], v187 offset:34816
	ds_read_b64_tr_b16 v[228:229], v187 offset:34848
	ds_read_b64_tr_b16 v[232:233], v193 offset:34848
	ds_read_b64_tr_b16 v[230:231], v187 offset:35936
	ds_read_b64_tr_b16 v[234:235], v187 offset:44640
	s_ashr_i32 s43, s42, 31
	s_lshl_b64 s[4:5], s[42:43], 10
	s_nop 2
	v_cvt_pk_bf16_f32 v112, v112, v113
	v_cvt_pk_bf16_f32 v113, v114, v115
	v_lshl_add_u64 v[114:115], v[126:127], 0, s[4:5]
	global_store_dwordx2 v[114:115], v[112:113], off
	ds_read_b64_tr_b16 v[114:115], v187 offset:44608
	ds_read_b64_tr_b16 v[112:113], v193 offset:34816
	v_pk_mul_f32 v[98:99], v[98:99], v[132:133] op_sel_hi:[1,0]
	v_pk_mul_f32 v[96:97], v[96:97], v[132:133] op_sel_hi:[1,0]
	v_pk_mul_f32 v[102:103], v[102:103], v[132:133] op_sel_hi:[1,0]
	v_pk_mul_f32 v[100:101], v[100:101], v[132:133] op_sel_hi:[1,0]
	s_waitcnt lgkmcnt(6)
	v_mfma_f32_16x16x32_bf16 v[96:99], v[224:227], v[108:111], v[96:99]
	s_waitcnt lgkmcnt(0)
	v_mfma_f32_16x16x32_bf16 v[96:99], v[112:115], v[104:107], v[96:99]
	s_mov_b64 s[4:5], 0x6000
	v_lshl_add_u64 v[142:143], v[142:143], 0, s[4:5]
	s_mov_b64 s[4:5], 0xc000
	v_mfma_f32_16x16x32_bf16 v[100:103], v[228:231], v[108:111], v[100:103]
	s_add_i32 s21, s21, 12
	s_addk_i32 s22, 0xc0
	s_addk_i32 s24, 0xff40
	v_mfma_f32_16x16x32_bf16 v[100:103], v[232:235], v[104:107], v[100:103]
	v_cvt_pk_bf16_f32 v104, v96, v97
	v_cvt_pk_bf16_f32 v105, v98, v99
	v_lshl_add_u64 v[144:145], v[144:145], 0, s[4:5]
	v_lshl_add_u64 v[146:147], v[146:147], 0, s[4:5]
	v_lshl_add_u64 v[148:149], v[148:149], 0, s[4:5]
	s_nop 2
	v_cvt_pk_bf16_f32 v106, v100, v101
	v_cvt_pk_bf16_f32 v107, v102, v103
	s_cmp_lt_u32 s26, 33
	s_mov_b32 s27, s26
	ds_write_b128 v156, v[104:107]
	s_cbranch_scc0 .LBB0_640
